# static priority raise, other half: s_setprio 1 for waves 0-3 across the prompt-attention key-block loop (A/B against the waves 4-7 build)
# speedup vs baseline: 1.0043x; 1.0043x over previous
; #define LAS __attribute__((address_space(3)))
; #define LDS_WAIT() asm volatile("s_waitcnt lgkmcnt(0)" ::: "memory")
; __device__ __forceinline__ void attn_unit(Frame& F, int b, int h, int qt, int kb_lo, int nkb, const bf16* QB, const bf16* KB, const bf16* VT, bf16* OUT, float bias2, f32x4* part, float* tpart) {
;     LAS bf16* Ks = (LAS bf16*)F.lds;
;     LAS bf16* Vs = (LAS bf16*)(F.lds + 34816);
;     const int w = F.wave, lane = F.lane, li = lane & 15, g = lane >> 4, tid = F.tid;
;     const int q0 = qt * 128 + w * 16, qpos = q0 + li;
;     bf16x8 qf[4];
;     { const bf16* qp = QB + (size_t)(b * SEQ + qpos) * BW + h * 128 + 8 * g;
; #pragma unroll
;       for (int ks = 0; ks < 4; ++ks) qf[ks] = *(const bf16x8*)(qp + 32 * ks); }
;     f32x4 oacc[8];
; #pragma unroll
;     for (int dt = 0; dt < 8; ++dt) oacc[dt] = (f32x4){0.f, 0.f, 0.f, 0.f};
;     float carry = 1.f;
;     const int kr0 = tid >> 4, kc0 = (tid & 15) * 8;
;     const int vr0 = tid >> 3, vc0 = (tid & 7) * 8;
;     const bf16* kg = KB + (size_t)(b * SEQ) * BW + h * 128 + kc0;
;     const bf16* vg = VT + (size_t)((b * 4 + h) * 128) * SEQ + vc0;
;     u32x4 lk[2], lv[2];
;     { const int kb = kb_lo + nkb - 1;
;       lk[0] = *(const u32x4*)(kg + (size_t)(kb * 64 + kr0) * BW); lk[1] = *(const u32x4*)(kg + (size_t)(kb * 64 + kr0 + 32) * BW);
;       lv[0] = *(const u32x4*)(vg + (size_t)vr0 * SEQ + kb * 64); lv[1] = *(const u32x4*)(vg + (size_t)(vr0 + 64) * SEQ + kb * 64);
;       *(LAS u32x4*)(Ks + kr0 * 136 + kc0) = lk[0]; *(LAS u32x4*)(Ks + (kr0 + 32) * 136 + kc0) = lk[1];
;       *(LAS u32x4*)(Vs + vr0 * 72 + vc0) = lv[0]; *(LAS u32x4*)(Vs + (vr0 + 64) * 72 + vc0) = lv[1]; }
;     LDS_WAIT(); __syncthreads();
.LBB0_1057:
	v_readlane_b32 s0, v252, 42
	s_lshl_b32 s20, s0, 1
	v_readlane_b32 s0, v252, 48
	v_lshlrev_b32_e64 v4, 4, s18
	v_readlane_b32 s1, v252, 49
	s_add_u32 s0, s10, s0
	v_lshl_add_u32 v118, s5, 7, v4
	v_lshlrev_b32_e32 v4, 3, v1
	s_addc_u32 s1, s11, s1
	v_and_b32_e32 v5, 0x78, v4
	s_add_u32 s0, s0, s20
	s_addc_u32 s1, s1, 0
	v_lshlrev_b32_e32 v34, 1, v5
	v_ashrrev_i32_e32 v119, 4, v1
	v_ashrrev_i32_e32 v20, 3, v1
	v_and_b32_e32 v1, 56, v4
	v_lshl_add_u64 v[4:5], s[0:1], 0, v[34:35]
	s_mov_b64 s[0:1], 0x33600000
	v_lshl_add_u64 v[78:79], v[4:5], 0, s[0:1]
	v_readlane_b32 s0, v252, 43
	v_readlane_b32 s1, v252, 44
	s_add_u32 s0, s10, s0
	s_addc_u32 s1, s11, s1
	s_add_i32 s19, s2, s4
	s_lshl_b32 s2, s19, 6
	v_add_u32_e32 v4, s2, v119
	v_ashrrev_i32_e32 v5, 31, v4
	v_lshlrev_b32_e32 v80, 1, v1
	v_mov_b32_e32 v81, v35
	v_lshlrev_b64 v[4:5], 10, v[4:5]
	v_ashrrev_i32_e32 v21, 31, v20
	v_lshl_add_u64 v[12:13], s[0:1], 0, v[80:81]
	v_lshl_add_u64 v[4:5], v[78:79], 0, v[4:5]
	s_mov_b32 s0, 0x8000
	v_lshlrev_b64 v[14:15], 13, v[20:21]
	v_add_co_u32_e32 v8, vcc, s0, v4
	v_lshl_add_u64 v[12:13], v[12:13], 0, v[14:15]
	s_mov_b64 s[0:1], 0x33e00000
	s_mov_b32 s3, s21
	s_mov_b64 s[6:7], 0x33e80000
	v_and_b32_e32 v3, 15, v122
	v_lshl_add_u64 v[82:83], v[12:13], 0, s[0:1]
	s_lshl_b64 s[0:1], s[2:3], 1
	v_lshl_add_u64 v[84:85], v[12:13], 0, s[6:7]
	v_lshl_add_u64 v[14:15], v[82:83], 0, s[0:1]
	v_lshl_add_u64 v[16:17], v[84:85], 0, s[0:1]
	v_or_b32_e32 v76, v118, v3
	v_readlane_b32 s0, v252, 46
	v_ashrrev_i32_e32 v30, 4, v122
	v_lshlrev_b32_e32 v26, 3, v30
	v_add_u32_e32 v22, s0, v76
	v_ashrrev_i32_e32 v23, 31, v22
	v_lshlrev_b64 v[24:25], 10, v[22:23]
	v_lshl_add_u64 v[24:25], s[10:11], 0, v[24:25]
	v_readlane_b32 s1, v252, 47
	v_lshl_add_u64 v[24:25], v[24:25], 0, s[20:21]
	v_ashrrev_i32_e32 v27, 31, v26
	v_addc_co_u32_e32 v9, vcc, 0, v5, vcc
	v_lshl_add_u64 v[24:25], v[26:27], 1, v[24:25]
	s_mov_b64 s[0:1], 0x32e00000
	global_load_dwordx4 v[4:7], v[4:5], off
	s_nop 0
	global_load_dwordx4 v[8:11], v[8:9], off
	s_nop 0
	global_load_dwordx4 v[12:15], v[14:15], off
	s_nop 0
	global_load_dwordx4 v[16:19], v[16:17], off
	v_lshl_add_u64 v[28:29], v[24:25], 0, s[0:1]
	s_mov_b32 s0, 0x32e00000
	v_add_co_u32_e32 v24, vcc, s0, v24
	s_movk_i32 s3, 0x88
	s_nop 0
	v_addc_co_u32_e32 v25, vcc, 0, v25, vcc
	global_load_dwordx4 v[44:47], v[28:29], off offset:64
	global_load_dwordx4 v[40:43], v[28:29], off offset:128
	global_load_dwordx4 v[48:51], v[24:25], off
	global_load_dwordx4 v[36:39], v[28:29], off offset:192
	s_waitcnt vmcnt(8)
	v_mul_f32_e32 v52, 0x3fb8aa3b, v2
	v_mul_lo_u32 v2, v119, s3
	s_movk_i32 s3, 0x48
	v_mul_lo_u32 v20, v20, s3
	v_lshlrev_b32_e32 v125, 1, v2
	v_lshlrev_b32_e32 v126, 1, v20
	v_add3_u32 v2, 0, v125, v34
	v_and_b32_e32 v1, -16, v122
	v_mul_u32_u24_e32 v121, 0x110, v3
	v_mul_u32_u24_e32 v73, 0x90, v3
	v_add3_u32 v3, 0, v126, v80
	v_add_u32_e32 v120, 0, v1
	v_lshlrev_b32_e32 v72, 2, v30
	v_cmp_ne_u32_e64 s[38:39], 1, v30
	v_cmp_eq_u32_e32 vcc, 2, v30
	v_sub_u32_e32 v77, v120, v26
	v_lshlrev_b64 v[74:75], 9, v[22:23]
	s_mov_b32 s24, 0
	v_cmp_lt_u32_e64 s[0:1], 15, v122
	v_mov_b32_e32 v53, v52
	v_mov_b32_e32 v54, v52
	v_mov_b32_e32 v55, v52
	v_or_b32_e32 v124, 15, v118
	v_mov_b32_e32 v1, v76
	s_add_i32 s25, s4, -1
	s_or_b32 s26, s2, 63
	s_waitcnt vmcnt(7)
	ds_write_b128 v2, v[4:7]
	s_waitcnt vmcnt(6)
	ds_write_b128 v2, v[8:11] offset:8704
	s_waitcnt vmcnt(5)
	ds_write_b128 v3, v[12:15] offset:34816
	s_waitcnt vmcnt(4)
	ds_write_b128 v3, v[16:19] offset:44032
	s_waitcnt lgkmcnt(0)
	v_mov_b32_e32 v4, v35
	v_mov_b32_e32 v5, v35
	v_mov_b32_e32 v2, v35
	v_mov_b32_e32 v3, v35
	v_mov_b64_e32 v[8:9], v[4:5]
	v_mov_b64_e32 v[12:13], v[4:5]
	v_mov_b64_e32 v[16:17], v[4:5]
	v_mov_b64_e32 v[20:21], v[4:5]
	v_mov_b64_e32 v[24:25], v[4:5]
	v_mov_b64_e32 v[28:29], v[4:5]
	v_mov_b64_e32 v[32:33], v[4:5]
	v_mov_b32_e32 v81, 1.0
	v_mov_b64_e32 v[6:7], v[2:3]
	v_mov_b64_e32 v[10:11], v[2:3]
	v_mov_b64_e32 v[14:15], v[2:3]
	v_mov_b64_e32 v[18:19], v[2:3]
	v_mov_b64_e32 v[22:23], v[2:3]
	v_mov_b64_e32 v[26:27], v[2:3]
	v_mov_b64_e32 v[30:31], v[2:3]
	s_cmp_lt_u32 s18, 4
	s_cbranch_scc0 .Lattn_prio_done
	s_setprio 1
